# v86 + HGRN2: gate loads issued at the end of step 2 ahead of the next chunk's v loads; step-5 counted waits leave the v loads in flight
# speedup vs baseline: 1.0047x; 1.0047x over previous
.LBB0_1168:
	s_or_b64 exec, exec, s[6:7]
	s_waitcnt lgkmcnt(0)
	ds_read_b128 v[114:117], v150 offset:52224
	ds_read_b128 v[118:121], v150 offset:52288
	v_add_u32_e32 v67, v137, v133
	ds_read_b128 v[160:163], v151
	ds_read_b128 v[164:167], v67
	ds_read_b128 v[168:171], v67 offset:2304
	ds_read_b128 v[172:175], v67 offset:64
	ds_read_b128 v[176:179], v67 offset:2368
	v_ashrrev_i32_e32 v67, 31, v66
	s_waitcnt lgkmcnt(4)
	v_pk_mul_f32 v[18:19], v[18:19], v[160:161]
	v_pk_mul_f32 v[20:21], v[20:21], v[162:163]
	v_pk_mul_f32 v[30:31], v[30:31], v[160:161]
	v_pk_mul_f32 v[32:33], v[32:33], v[162:163]
	s_waitcnt lgkmcnt(3)
	v_mfma_f32_16x16x32_bf16 v[18:21], v[114:117], v[164:167], v[18:21]
	s_waitcnt lgkmcnt(2)
	v_mfma_f32_16x16x32_bf16 v[30:33], v[114:117], v[168:171], v[30:33]
	s_waitcnt lgkmcnt(1)
	v_mfma_f32_16x16x32_bf16 v[18:21], v[118:121], v[172:175], v[18:21]
	s_waitcnt lgkmcnt(0)
	v_mfma_f32_16x16x32_bf16 v[30:33], v[118:121], v[176:179], v[30:33]
	ds_read_b128 v[164:167], v152
	ds_read_b128 v[168:171], v152 offset:2304
	ds_read_b128 v[172:175], v152 offset:64
	ds_read_b128 v[176:179], v152 offset:2368
	v_pk_mul_f32 v[34:35], v[34:35], v[160:161]
	v_pk_mul_f32 v[36:37], v[36:37], v[162:163]
	v_pk_mul_f32 v[38:39], v[38:39], v[160:161]
	v_pk_mul_f32 v[40:41], v[40:41], v[162:163]
	s_waitcnt lgkmcnt(3)
	v_mfma_f32_16x16x32_bf16 v[34:37], v[114:117], v[164:167], v[34:37]
	s_waitcnt lgkmcnt(2)
	v_mfma_f32_16x16x32_bf16 v[38:41], v[114:117], v[168:171], v[38:41]
	s_waitcnt lgkmcnt(1)
	v_mfma_f32_16x16x32_bf16 v[34:37], v[118:121], v[172:175], v[34:37]
	s_waitcnt lgkmcnt(0)
	v_mfma_f32_16x16x32_bf16 v[38:41], v[118:121], v[176:179], v[38:41]
	ds_read_b128 v[164:167], v153
	ds_read_b128 v[168:171], v153 offset:2304
	ds_read_b128 v[172:175], v153 offset:64
	ds_read_b128 v[176:179], v153 offset:2368
	v_pk_mul_f32 v[42:43], v[42:43], v[160:161]
	v_pk_mul_f32 v[44:45], v[44:45], v[162:163]
	v_pk_mul_f32 v[50:51], v[50:51], v[160:161]
	v_pk_mul_f32 v[52:53], v[52:53], v[162:163]
	s_waitcnt lgkmcnt(3)
	v_mfma_f32_16x16x32_bf16 v[42:45], v[114:117], v[164:167], v[42:45]
	s_waitcnt lgkmcnt(2)
	v_mfma_f32_16x16x32_bf16 v[50:53], v[114:117], v[168:171], v[50:53]
	s_waitcnt lgkmcnt(1)
	v_mfma_f32_16x16x32_bf16 v[42:45], v[118:121], v[172:175], v[42:45]
	s_waitcnt lgkmcnt(0)
	v_mfma_f32_16x16x32_bf16 v[50:53], v[118:121], v[176:179], v[50:53]
	ds_read_b128 v[164:167], v154
	ds_read_b128 v[168:171], v154 offset:2304
	ds_read_b128 v[172:175], v154 offset:64
	ds_read_b128 v[176:179], v154 offset:2368
	v_pk_mul_f32 v[46:47], v[46:47], v[160:161]
	v_pk_mul_f32 v[48:49], v[48:49], v[162:163]
	v_pk_mul_f32 v[54:55], v[54:55], v[160:161]
	v_pk_mul_f32 v[56:57], v[56:57], v[162:163]
	s_waitcnt lgkmcnt(3)
	v_mfma_f32_16x16x32_bf16 v[46:49], v[114:117], v[164:167], v[46:49]
	s_waitcnt lgkmcnt(0)
	s_barrier
	v_mfma_f32_16x16x32_bf16 v[54:57], v[114:117], v[168:171], v[54:57]
	ds_read2st64_b32 v[114:115], v136 offset1:1
	v_lshlrev_b64 v[66:67], 13, v[66:67]
	s_waitcnt vmcnt(5)
	v_mov_b32_e32 v64, v180
	v_mov_b32_e32 v65, v181
	v_lshlrev_b32_e32 v116, 16, v64
	v_and_b32_e32 v117, 0xffff0000, v64
	v_lshl_add_u64 v[66:67], s[4:5], 0, v[66:67]
	s_waitcnt lgkmcnt(0)
	v_add_f32_e32 v114, v114, v115
	v_fmamk_f32 v114, v114, 0x3c000000, v197
	v_cmp_gt_f32_e32 vcc, s81, v114
	v_mul_f32_e32 v115, 0x4b800000, v114
	v_lshl_add_u64 v[66:67], v[66:67], 0, s[36:37]
	v_cndmask_b32_e32 v114, v114, v115, vcc
	v_rsq_f32_e32 v114, v114
	s_mov_b64 s[6:7], 0x29401000
	v_lshl_add_u64 v[66:67], v[66:67], 0, s[6:7]
	v_mfma_f32_16x16x32_bf16 v[46:49], v[118:121], v[172:175], v[46:49]
	v_mul_f32_e32 v115, 0x45800000, v114
	v_cndmask_b32_e32 v114, v114, v115, vcc
	v_pk_mul_f32 v[70:71], v[70:71], v[114:115] op_sel_hi:[1,0]
	v_pk_mul_f32 v[68:69], v[68:69], v[114:115] op_sel_hi:[1,0]
	v_pk_mul_f32 v[70:71], v[2:3], v[70:71]
	v_pk_mul_f32 v[68:69], v[4:5], v[68:69]
	v_pk_mul_f32 v[70:71], v[70:71], v[116:117]
	v_mfma_f32_16x16x32_bf16 v[54:57], v[118:121], v[176:179], v[54:57]
	v_cvt_pk_bf16_f32 v64, v70, v71
	v_lshlrev_b32_e32 v70, 16, v65
	v_and_b32_e32 v71, 0xffff0000, v65
	v_pk_mul_f32 v[68:69], v[68:69], v[70:71]
	s_waitcnt vmcnt(4)
	v_mov_b32_e32 v62, v182
	v_mov_b32_e32 v63, v183
	v_lshlrev_b32_e32 v70, 16, v62
	v_cvt_pk_bf16_f32 v65, v68, v69
	v_lshl_add_u64 v[68:69], v[94:95], 1, v[66:67]
	global_store_dwordx2 v[68:69], v[64:65], off
	v_pk_mul_f32 v[64:65], v[104:105], v[114:115] op_sel_hi:[1,0]
	v_and_b32_e32 v71, 0xffff0000, v62
	v_pk_mul_f32 v[64:65], v[6:7], v[64:65]
	v_pk_mul_f32 v[68:69], v[72:73], v[114:115] op_sel_hi:[1,0]
	v_pk_mul_f32 v[64:65], v[64:65], v[70:71]
	v_pk_mul_f32 v[68:69], v[8:9], v[68:69]
	v_cvt_pk_bf16_f32 v62, v64, v65
	v_lshlrev_b32_e32 v64, 16, v63
	v_and_b32_e32 v65, 0xffff0000, v63
	v_pk_mul_f32 v[64:65], v[68:69], v[64:65]
	s_waitcnt vmcnt(4)
	v_mov_b32_e32 v60, v184
	v_mov_b32_e32 v61, v185
	v_lshlrev_b32_e32 v68, 16, v60
	v_cvt_pk_bf16_f32 v63, v64, v65
	v_lshl_add_u64 v[64:65], v[98:99], 1, v[66:67]
	global_store_dwordx2 v[64:65], v[62:63], off offset:32
	v_pk_mul_f32 v[62:63], v[108:109], v[114:115] op_sel_hi:[1,0]
	v_and_b32_e32 v69, 0xffff0000, v60
	v_pk_mul_f32 v[62:63], v[10:11], v[62:63]
	v_pk_mul_f32 v[66:67], v[106:107], v[114:115] op_sel_hi:[1,0]
	v_pk_mul_f32 v[62:63], v[62:63], v[68:69]
	v_pk_mul_f32 v[66:67], v[12:13], v[66:67]
	v_cvt_pk_bf16_f32 v60, v62, v63
	v_lshlrev_b32_e32 v62, 16, v61
	v_and_b32_e32 v63, 0xffff0000, v61
	v_pk_mul_f32 v[62:63], v[66:67], v[62:63]
	s_waitcnt vmcnt(4)
	v_mov_b32_e32 v58, v186
	v_mov_b32_e32 v59, v187
	v_lshlrev_b32_e32 v66, 16, v58
	v_cvt_pk_bf16_f32 v61, v62, v63
	global_store_dwordx2 v[64:65], v[60:61], off offset:64
	v_pk_mul_f32 v[60:61], v[112:113], v[114:115] op_sel_hi:[1,0]
	v_and_b32_e32 v67, 0xffff0000, v58
	v_pk_mul_f32 v[60:61], v[14:15], v[60:61]
	v_pk_mul_f32 v[62:63], v[110:111], v[114:115] op_sel_hi:[1,0]
	v_pk_mul_f32 v[60:61], v[60:61], v[66:67]
	v_pk_mul_f32 v[62:63], v[16:17], v[62:63]
	v_cvt_pk_bf16_f32 v58, v60, v61
	v_lshlrev_b32_e32 v60, 16, v59
	v_and_b32_e32 v61, 0xffff0000, v59
	v_pk_mul_f32 v[60:61], v[62:63], v[60:61]
	s_cmp_lg_u32 s3, 32
	v_cvt_pk_bf16_f32 v59, v60, v61
	global_store_dwordx2 v[64:65], v[58:59], off offset:96
	v_cvt_pk_bf16_f32 v58, v18, v19
	v_cvt_pk_bf16_f32 v59, v20, v21
	ds_write_b64 v155, v[58:59]
	v_cvt_pk_bf16_f32 v58, v30, v31
	v_cvt_pk_bf16_f32 v59, v32, v33
	ds_write_b64 v155, v[58:59] offset:4352
	v_cvt_pk_bf16_f32 v58, v34, v35
	v_cvt_pk_bf16_f32 v59, v36, v37
	ds_write_b64 v155, v[58:59] offset:8704
	v_cvt_pk_bf16_f32 v58, v38, v39
	v_cvt_pk_bf16_f32 v59, v40, v41
	ds_write_b64 v155, v[58:59] offset:13056
	v_cvt_pk_bf16_f32 v58, v42, v43
	v_cvt_pk_bf16_f32 v59, v44, v45
	ds_write_b64 v155, v[58:59] offset:17408
	v_cvt_pk_bf16_f32 v58, v50, v51
	v_cvt_pk_bf16_f32 v59, v52, v53
	ds_write_b64 v155, v[58:59] offset:21760
	v_cvt_pk_bf16_f32 v58, v46, v47
	v_cvt_pk_bf16_f32 v59, v48, v49
	ds_write_b64 v155, v[58:59] offset:26112
	v_cvt_pk_bf16_f32 v58, v54, v55
	v_cvt_pk_bf16_f32 v59, v56, v57
	s_mov_b32 s2, s3
	ds_write_b64 v155, v[58:59] offset:30464
	s_cbranch_scc0 .LBB0_1179

.LBB0_1173:
	v_readlane_b32 s6, v254, 18
	v_readlane_b32 s7, v254, 19
	s_mul_i32 s3, s20, 0x880
	s_nop 0
	v_cndmask_b32_e64 v123, v123, 0, s[6:7]
	v_cndmask_b32_e64 v122, v122, 0, s[6:7]
	v_readlane_b32 s6, v254, 26
	v_pk_add_f32 v[72:73], v[72:73], v[122:123]
	v_readlane_b32 s7, v254, 27
	s_nop 1
	v_cndmask_b32_e64 v73, v123, v73, s[6:7]
	v_cndmask_b32_e64 v72, v122, v72, s[6:7]
	v_readlane_b32 s6, v254, 28
	v_pk_add_f32 v[66:67], v[66:67], v[72:73]
	v_readlane_b32 s7, v254, 29
	s_nop 1
	v_cndmask_b32_e64 v67, v73, v67, s[6:7]
	v_cndmask_b32_e64 v66, v72, v66, s[6:7]
	v_readlane_b32 s6, v254, 30
	v_pk_add_f32 v[68:69], v[68:69], v[66:67]
	v_readlane_b32 s7, v254, 31
	s_nop 1
	v_cndmask_b32_e64 v67, v67, v69, s[6:7]
	v_cndmask_b32_e64 v66, v66, v68, s[6:7]
	v_readlane_b32 s6, v254, 32
	v_pk_add_f32 v[62:63], v[62:63], v[66:67]
	v_readlane_b32 s7, v254, 33
	v_and_b32_e32 v69, 0xffff0000, v125
	v_lshlrev_b32_e32 v68, 16, v125
	v_cndmask_b32_e64 v63, v67, v63, s[6:7]
	v_cndmask_b32_e64 v62, v66, v62, s[6:7]
	v_readlane_b32 s6, v254, 34
	v_pk_add_f32 v[64:65], v[64:65], v[62:63]
	v_readlane_b32 s7, v254, 35
	v_lshlrev_b32_e32 v66, 16, v75
	v_and_b32_e32 v67, 0xffff0000, v75
	s_mov_b32 s10, s8
	s_mul_i32 s10, s10, 0x6000
	s_mov_b32 s11, 0
	v_lshl_add_u64 v[238:239], v[78:79], 0, s[10:11]
	global_load_dword v75, v[238:239], off nt
	s_add_u32 s10, s10, 0x1000
	v_lshl_add_u64 v[240:241], v[78:79], 0, s[10:11]
	global_load_dword v125, v[240:241], off nt
	v_cndmask_b32_e64 v63, v63, v65, s[6:7]
	v_cndmask_b32_e64 v62, v62, v64, s[6:7]
	v_readlane_b32 s6, v254, 36
	v_pk_add_f32 v[58:59], v[58:59], v[62:63]
	v_readlane_b32 s7, v254, 37
	s_nop 1
	v_cndmask_b32_e64 v59, v63, v59, s[6:7]
	v_cndmask_b32_e64 v58, v62, v58, s[6:7]
	v_readlane_b32 s6, v254, 40
	v_pk_add_f32 v[60:61], v[60:61], v[58:59]
	v_readlane_b32 s7, v254, 41
	s_nop 1
	v_cndmask_b32_e64 v58, v58, v60, s[6:7]
	v_sub_f32_e32 v60, v120, v70
	v_cndmask_b32_e64 v59, v59, v61, s[6:7]
	v_exp_f32_e32 v64, v60
	v_sub_f32_e32 v60, v121, v71
	v_exp_f32_e32 v65, v60
	v_pk_add_f32 v[60:61], v[118:119], v[58:59]
	s_nop 0
	v_pk_add_f32 v[62:63], v[60:61], v[70:71] neg_lo:[0,1] neg_hi:[0,1]
	v_exp_f32_e32 v60, v60
	v_min_f32_e32 v73, 0x42e60000, v63
	v_min_f32_e64 v63, -v63, s14
	v_min_f32_e32 v72, 0x42e60000, v62
	v_min_f32_e64 v62, -v62, s14
	v_exp_f32_e32 v63, v63
	v_exp_f32_e32 v72, v72
	v_exp_f32_e32 v73, v73
	v_exp_f32_e32 v62, v62
	v_exp_f32_e32 v61, v61
	v_mul_f32_e32 v63, v63, v69
	v_add_u32_e32 v69, s3, v0
	v_mul_f32_e32 v60, v60, v66
	v_mul_f32_e32 v72, v72, v66
	v_mul_f32_e32 v73, v73, v67
	v_mul_f32_e32 v62, v62, v68
	v_cvt_pk_bf16_f32 v68, v72, v73
	ds_write_b32 v69, v68
	v_mul_f32_e32 v61, v61, v67
	v_cvt_pk_bf16_f32 v60, v60, v61
	ds_write_b32 v69, v60 offset:17408
	v_cvt_pk_bf16_f32 v60, v62, v63
	ds_write_b32 v69, v60 offset:34816
	v_pk_add_f32 v[60:61], v[116:117], v[58:59]
	v_mul_f32_e32 v66, v64, v62
	v_mul_f32_e32 v67, v63, v65
	v_pk_add_f32 v[62:63], v[60:61], v[70:71] neg_lo:[0,1] neg_hi:[0,1]
	v_exp_f32_e32 v60, v60
	v_min_f32_e32 v117, 0x42e60000, v62
	v_min_f32_e32 v118, 0x42e60000, v63
	v_min_f32_e64 v62, -v62, s14
	v_exp_f32_e32 v117, v117
	v_exp_f32_e32 v118, v118
	v_exp_f32_e32 v62, v62
	v_min_f32_e64 v63, -v63, s14
	v_exp_f32_e32 v61, v61
	v_exp_f32_e32 v63, v63
	v_lshlrev_b32_e32 v68, 16, v126
	v_and_b32_e32 v72, 0xffff0000, v126
	v_lshlrev_b32_e32 v73, 16, v127
	v_mul_f32_e32 v60, v60, v68
	v_and_b32_e32 v116, 0xffff0000, v127
	s_or_b32 s10, s8, 1
	s_mul_i32 s10, s10, 0x6000
	s_mov_b32 s11, 0
	v_lshl_add_u64 v[238:239], v[78:79], 0, s[10:11]
	global_load_dword v126, v[238:239], off nt
	s_add_u32 s10, s10, 0x1000
	v_lshl_add_u64 v[240:241], v[78:79], 0, s[10:11]
	global_load_dword v127, v[240:241], off nt
	v_mul_f32_e32 v117, v117, v68
	v_mul_f32_e32 v118, v118, v72
	v_mul_f32_e32 v62, v62, v73
	v_cvt_pk_bf16_f32 v73, v117, v118
	ds_write_b32 v69, v73 offset:272
	v_mul_f32_e32 v61, v61, v72
	v_cvt_pk_bf16_f32 v60, v60, v61
	v_mul_f32_e32 v63, v63, v116
	ds_write_b32 v69, v60 offset:17680
	v_cvt_pk_bf16_f32 v60, v62, v63
	ds_write_b32 v69, v60 offset:35088
	v_pk_add_f32 v[60:61], v[114:115], v[58:59]
	v_mul_f32_e32 v68, v64, v62
	v_mul_f32_e32 v72, v63, v65
	v_pk_add_f32 v[62:63], v[60:61], v[70:71] neg_lo:[0,1] neg_hi:[0,1]
	v_exp_f32_e32 v60, v60
	v_min_f32_e32 v117, 0x42e60000, v62
	v_min_f32_e32 v118, 0x42e60000, v63
	v_min_f32_e64 v62, -v62, s14
	v_exp_f32_e32 v117, v117
	v_exp_f32_e32 v118, v118
	v_exp_f32_e32 v62, v62
	v_min_f32_e64 v63, -v63, s14
	v_exp_f32_e32 v61, v61
	v_exp_f32_e32 v63, v63
	v_lshlrev_b32_e32 v73, 16, v128
	v_and_b32_e32 v114, 0xffff0000, v128
	v_lshlrev_b32_e32 v115, 16, v129
	v_mul_f32_e32 v60, v60, v73
	v_and_b32_e32 v116, 0xffff0000, v129
	s_or_b32 s10, s8, 2
	s_mul_i32 s10, s10, 0x6000
	s_mov_b32 s11, 0
	v_lshl_add_u64 v[238:239], v[78:79], 0, s[10:11]
	global_load_dword v128, v[238:239], off nt
	s_add_u32 s10, s10, 0x1000
	v_lshl_add_u64 v[240:241], v[78:79], 0, s[10:11]
	global_load_dword v129, v[240:241], off nt
	v_mul_f32_e32 v117, v117, v73
	v_mul_f32_e32 v118, v118, v114
	v_mul_f32_e32 v62, v62, v115
	v_cvt_pk_bf16_f32 v115, v117, v118
	ds_write_b32 v69, v115 offset:544
	v_mul_f32_e32 v61, v61, v114
	v_cvt_pk_bf16_f32 v60, v60, v61
	v_mul_f32_e32 v63, v63, v116
	ds_write_b32 v69, v60 offset:17952
	v_cvt_pk_bf16_f32 v60, v62, v63
	ds_write_b32 v69, v60 offset:35360
	v_pk_add_f32 v[60:61], v[112:113], v[58:59]
	v_mul_f32_e32 v73, v64, v62
	v_mul_f32_e32 v114, v63, v65
	v_pk_add_f32 v[62:63], v[60:61], v[70:71] neg_lo:[0,1] neg_hi:[0,1]
	v_exp_f32_e32 v60, v60
	v_min_f32_e32 v117, 0x42e60000, v62
	v_min_f32_e32 v118, 0x42e60000, v63
	v_min_f32_e64 v62, -v62, s14
	v_exp_f32_e32 v117, v117
	v_exp_f32_e32 v118, v118
	v_exp_f32_e32 v62, v62
	v_min_f32_e64 v63, -v63, s14
	v_exp_f32_e32 v61, v61
	v_exp_f32_e32 v63, v63
	v_lshlrev_b32_e32 v112, 16, v130
	v_and_b32_e32 v113, 0xffff0000, v130
	v_lshlrev_b32_e32 v115, 16, v131
	v_mul_f32_e32 v60, v60, v112
	v_and_b32_e32 v116, 0xffff0000, v131
	s_or_b32 s10, s8, 3
	s_mul_i32 s10, s10, 0x6000
	s_mov_b32 s11, 0
	v_lshl_add_u64 v[238:239], v[78:79], 0, s[10:11]
	global_load_dword v130, v[238:239], off nt
	s_add_u32 s10, s10, 0x1000
	v_lshl_add_u64 v[240:241], v[78:79], 0, s[10:11]
	global_load_dword v131, v[240:241], off nt
	v_mul_f32_e32 v117, v117, v112
	v_mul_f32_e32 v118, v118, v113
	v_mul_f32_e32 v62, v62, v115
	v_cvt_pk_bf16_f32 v115, v117, v118
	ds_write_b32 v69, v115 offset:816
	v_mul_f32_e32 v61, v61, v113
	v_cvt_pk_bf16_f32 v60, v60, v61
	v_mul_f32_e32 v63, v63, v116
	ds_write_b32 v69, v60 offset:18224
	v_cvt_pk_bf16_f32 v60, v62, v63
	ds_write_b32 v69, v60 offset:35632
	v_pk_add_f32 v[60:61], v[110:111], v[58:59]
	v_mul_f32_e32 v112, v64, v62
	v_mul_f32_e32 v113, v63, v65
	v_pk_add_f32 v[62:63], v[60:61], v[70:71] neg_lo:[0,1] neg_hi:[0,1]
	v_exp_f32_e32 v60, v60
	v_min_f32_e32 v117, 0x42e60000, v62
	v_min_f32_e32 v118, 0x42e60000, v63
	v_min_f32_e64 v62, -v62, s14
	v_exp_f32_e32 v117, v117
	v_exp_f32_e32 v118, v118
	v_exp_f32_e32 v62, v62
	v_min_f32_e64 v63, -v63, s14
	v_exp_f32_e32 v61, v61
	v_exp_f32_e32 v63, v63
	v_lshlrev_b32_e32 v110, 16, v140
	v_and_b32_e32 v111, 0xffff0000, v140
	v_lshlrev_b32_e32 v115, 16, v142
	v_mul_f32_e32 v60, v60, v110
	v_and_b32_e32 v116, 0xffff0000, v142
	s_or_b32 s10, s8, 4
	s_mul_i32 s10, s10, 0x6000
	s_mov_b32 s11, 0
	v_lshl_add_u64 v[238:239], v[78:79], 0, s[10:11]
	global_load_dword v140, v[238:239], off nt
	s_add_u32 s10, s10, 0x1000
	v_lshl_add_u64 v[240:241], v[78:79], 0, s[10:11]
	global_load_dword v142, v[240:241], off nt
	v_mul_f32_e32 v117, v117, v110
	v_mul_f32_e32 v118, v118, v111
	v_mul_f32_e32 v62, v62, v115
	v_cvt_pk_bf16_f32 v115, v117, v118
	ds_write_b32 v69, v115 offset:1088
	v_mul_f32_e32 v61, v61, v111
	v_cvt_pk_bf16_f32 v60, v60, v61
	v_mul_f32_e32 v63, v63, v116
	ds_write_b32 v69, v60 offset:18496
	v_cvt_pk_bf16_f32 v60, v62, v63
	ds_write_b32 v69, v60 offset:35904
	v_pk_add_f32 v[60:61], v[108:109], v[58:59]
	v_mul_f32_e32 v110, v64, v62
	v_mul_f32_e32 v111, v63, v65
	v_pk_add_f32 v[62:63], v[60:61], v[70:71] neg_lo:[0,1] neg_hi:[0,1]
	v_exp_f32_e32 v60, v60
	v_min_f32_e32 v117, 0x42e60000, v62
	v_min_f32_e32 v118, 0x42e60000, v63
	v_min_f32_e64 v62, -v62, s14
	v_exp_f32_e32 v117, v117
	v_exp_f32_e32 v118, v118
	v_exp_f32_e32 v62, v62
	v_min_f32_e64 v63, -v63, s14
	v_exp_f32_e32 v61, v61
	v_exp_f32_e32 v63, v63
	v_lshlrev_b32_e32 v108, 16, v144
	v_and_b32_e32 v109, 0xffff0000, v144
	v_lshlrev_b32_e32 v115, 16, v149
	v_mul_f32_e32 v60, v60, v108
	v_and_b32_e32 v116, 0xffff0000, v149
	s_or_b32 s10, s8, 5
	s_mul_i32 s10, s10, 0x6000
	s_mov_b32 s11, 0
	v_lshl_add_u64 v[238:239], v[78:79], 0, s[10:11]
	global_load_dword v144, v[238:239], off nt
	s_add_u32 s10, s10, 0x1000
	v_lshl_add_u64 v[240:241], v[78:79], 0, s[10:11]
	global_load_dword v149, v[240:241], off nt
	v_mul_f32_e32 v117, v117, v108
	v_mul_f32_e32 v118, v118, v109
	v_mul_f32_e32 v62, v62, v115
	v_cvt_pk_bf16_f32 v115, v117, v118
	ds_write_b32 v69, v115 offset:1360
	v_mul_f32_e32 v61, v61, v109
	v_cvt_pk_bf16_f32 v60, v60, v61
	v_mul_f32_e32 v63, v63, v116
	ds_write_b32 v69, v60 offset:18768
	v_cvt_pk_bf16_f32 v60, v62, v63
	ds_write_b32 v69, v60 offset:36176
	v_pk_add_f32 v[60:61], v[106:107], v[58:59]
	v_mul_f32_e32 v108, v64, v62
	v_mul_f32_e32 v109, v63, v65
	v_pk_add_f32 v[62:63], v[60:61], v[70:71] neg_lo:[0,1] neg_hi:[0,1]
	v_exp_f32_e32 v60, v60
	v_min_f32_e32 v117, 0x42e60000, v62
	v_min_f32_e32 v118, 0x42e60000, v63
	v_min_f32_e64 v62, -v62, s14
	v_exp_f32_e32 v117, v117
	v_exp_f32_e32 v118, v118
	v_exp_f32_e32 v62, v62
	v_min_f32_e64 v63, -v63, s14
	v_exp_f32_e32 v61, v61
	v_exp_f32_e32 v63, v63
	v_lshlrev_b32_e32 v106, 16, v156
	v_and_b32_e32 v107, 0xffff0000, v156
	v_lshlrev_b32_e32 v115, 16, v157
	v_mul_f32_e32 v60, v60, v106
	v_and_b32_e32 v116, 0xffff0000, v157
	s_or_b32 s10, s8, 6
	s_mul_i32 s10, s10, 0x6000
	s_mov_b32 s11, 0
	v_lshl_add_u64 v[238:239], v[78:79], 0, s[10:11]
	global_load_dword v156, v[238:239], off nt
	s_add_u32 s10, s10, 0x1000
	v_lshl_add_u64 v[240:241], v[78:79], 0, s[10:11]
	global_load_dword v157, v[240:241], off nt
	v_mul_f32_e32 v117, v117, v106
	v_mul_f32_e32 v118, v118, v107
	v_mul_f32_e32 v62, v62, v115
	v_cvt_pk_bf16_f32 v115, v117, v118
	ds_write_b32 v69, v115 offset:1632
	v_mul_f32_e32 v61, v61, v107
	v_cvt_pk_bf16_f32 v60, v60, v61
	v_mul_f32_e32 v63, v63, v116
	ds_write_b32 v69, v60 offset:19040
	v_cvt_pk_bf16_f32 v60, v62, v63
	v_pk_add_f32 v[58:59], v[104:105], v[58:59]
	ds_write_b32 v69, v60 offset:36448
	v_pk_add_f32 v[60:61], v[58:59], v[70:71] neg_lo:[0,1] neg_hi:[0,1]
	v_exp_f32_e32 v58, v58
	v_min_f32_e32 v106, 0x42e60000, v60
	v_min_f32_e32 v107, 0x42e60000, v61
	v_min_f32_e64 v60, -v60, s14
	v_exp_f32_e32 v106, v106
	v_exp_f32_e32 v107, v107
	v_exp_f32_e32 v60, v60
	v_min_f32_e64 v61, -v61, s14
	v_exp_f32_e32 v59, v59
	v_exp_f32_e32 v61, v61
	v_lshlrev_b32_e32 v70, 16, v158
	v_and_b32_e32 v71, 0xffff0000, v158
	v_lshlrev_b32_e32 v104, 16, v159
	v_mul_f32_e32 v58, v58, v70
	v_and_b32_e32 v105, 0xffff0000, v159
	s_or_b32 s10, s8, 7
	s_mul_i32 s10, s10, 0x6000
	s_mov_b32 s11, 0
	v_lshl_add_u64 v[238:239], v[78:79], 0, s[10:11]
	global_load_dword v158, v[238:239], off nt
	s_add_u32 s10, s10, 0x1000
	v_lshl_add_u64 v[240:241], v[78:79], 0, s[10:11]
	global_load_dword v159, v[240:241], off nt
	v_mul_f32_e32 v106, v106, v70
	v_mul_f32_e32 v107, v107, v71
	v_mul_f32_e32 v60, v60, v104
	v_cvt_pk_bf16_f32 v104, v106, v107
	ds_write_b32 v69, v104 offset:1904
	v_mul_f32_e32 v59, v59, v71
	v_cvt_pk_bf16_f32 v58, v58, v59
	v_mul_f32_e32 v61, v61, v105
	ds_write_b32 v69, v58 offset:19312
	v_cvt_pk_bf16_f32 v58, v60, v61
	ds_write_b32 v69, v58 offset:36720
	v_cvt_pk_bf16_f32 v58, v66, v68
	v_mul_f32_e32 v62, v64, v62
	v_mul_f32_e32 v63, v63, v65
	v_mul_f32_e32 v64, v64, v60
	v_mul_f32_e32 v65, v61, v65
	v_cvt_pk_bf16_f32 v59, v73, v112
	v_cvt_pk_bf16_f32 v60, v110, v108
	v_cvt_pk_bf16_f32 v61, v62, v64
	ds_write_b128 v143, v[58:61] offset:52224
	v_cvt_pk_bf16_f32 v58, v67, v72
	s_add_i32 s3, s2, 1
	v_cvt_pk_bf16_f32 v59, v114, v113
	v_cvt_pk_bf16_f32 v60, v111, v109
	v_cvt_pk_bf16_f32 v61, v63, v65
	ds_write_b128 v143, v[58:61] offset:52368
	v_add_u32_e32 v58, s19, v74
	s_cmp_eq_u32 s2, 31
	ds_write_b16 v58, v22
	ds_write_b16_d16_hi v58, v22 offset:144
	ds_write_b16 v58, v23 offset:288
	ds_write_b16_d16_hi v58, v23 offset:432
	ds_write_b16 v58, v24 offset:576
	ds_write_b16_d16_hi v58, v24 offset:720
	ds_write_b16 v58, v25 offset:864
	ds_write_b16_d16_hi v58, v25 offset:1008
	s_waitcnt vmcnt(28)
	ds_write_b16 v58, v26 offset:1152
	ds_write_b16_d16_hi v58, v26 offset:1296
	ds_write_b16 v58, v27 offset:1440
	ds_write_b16_d16_hi v58, v27 offset:1584
	ds_write_b16 v58, v28 offset:1728
	ds_write_b16_d16_hi v58, v28 offset:1872
	ds_write_b16 v58, v29 offset:2016
	ds_write_b16_d16_hi v58, v29 offset:2160
	v_lshl_add_u32 v242, s2, 6, v138
	v_mov_b64_e32 v[238:239], s[0:1]
	v_mad_i64_i32 v[238:239], s[6:7], v242, s28, v[238:239]
	v_readlane_b32 s6, v254, 47
	v_lshl_add_u64 v[238:239], v[238:239], 0, s[36:37]
	v_lshl_add_u64 v[238:239], v[88:89], 1, v[238:239]
	s_nop 0
	s_lshl_b32 s6, s6, 1
	s_mov_b32 s7, s37
	v_lshl_add_u64 v[238:239], v[238:239], 0, s[6:7]
	s_mov_b64 s[6:7], 0x5000
	v_lshl_add_u64 v[240:241], v[238:239], 0, s[6:7]
	v_add_co_u32_e32 v238, vcc, s13, v238
	s_nop 1
	v_addc_co_u32_e32 v239, vcc, 0, v239, vcc
	global_load_dwordx2 v[180:181], v[238:239], off
	global_load_dwordx2 v[182:183], v[240:241], off offset:32
	global_load_dwordx2 v[184:185], v[240:241], off offset:64
	global_load_dwordx2 v[186:187], v[240:241], off offset:96
	s_mul_i32 s10, s8, 0x6000
	s_mov_b32 s11, 0
	v_lshl_add_u64 v[240:241], v[84:85], 0, s[10:11]
	global_load_dwordx4 v[22:25], v[240:241], off
	global_load_dwordx4 v[26:29], v[240:241], off offset:16
